# cross-attention LDS loop: row max by a 3-input max tree, next tile's K fragments read during the softmax
# speedup vs baseline: 1.0041x; 1.0041x over previous
; __device__ __forceinline__ void xattn_phase(const bf16* QXB, const bf16* MKF, const bf16* MVF, bf16* OXB, int G, int tid) {
;     ...
;     for (int it = (int)blockIdx.x * (MK_THREADS / 64) + wave; it < NIT; it += G * (MK_THREADS / 64)) { const int qb = it % NQ32, bhx = it / NQ32, h = bhx % XH, b = bhx / XH;
;         const size_t row0 = (size_t)b * SEQ + 32 * qb;
;         const bf16* qp = QXB + (row0 + r32) * XW + h * XHD + 8 * hh; const bf16* kp = MKF + (size_t)(b * XH + h) * 32768 + lane * 8;
;         bf16x8 qf[8];
; #pragma unroll
;         for (int ks = 0; ks < 8; ++ks) qf[ks] = *(const bf16x8*)(qp + 16 * ks);
;         const bf16* vp = MVF + (size_t)(b * XH + h) * 32768 + lane * 16;
;         f32x16 o[4]; o[0] = f32x16{}; o[1] = f32x16{}; o[2] = f32x16{}; o[3] = f32x16{}; float m_run = -INFINITY, l_run = 0.f;
;     ...
;         bf16x8 kfa[8], kfb[8];
; #pragma unroll
;         for (int ks = 0; ks < 8; ++ks) kfa[ks] = *(const bf16x8*)(kp + ks * 512);
.LBB0_1511:
	s_ashr_i32 s0, s8, 31
	s_lshr_b32 s1, s0, 25
	s_add_i32 s1, s8, s1
	s_ashr_i32 s2, s1, 7
	s_and_b32 s1, s1, 0x7ffff80
	s_sub_i32 s6, s8, s1
	s_lshr_b32 s1, s2, 30
	s_add_i32 s1, s2, s1
	s_lshr_b32 s0, s0, 23
	s_and_b32 s1, s1, -4
	s_add_i32 s0, s8, s0
	s_sub_i32 s7, s2, s1
	s_ashr_i32 s2, s0, 9
	s_ashr_i32 s3, s2, 31
	s_lshl_b64 s[0:1], s[2:3], 12
	s_lshl_b32 s3, s6, 5
	s_ashr_i32 s6, s3, 31
	s_add_u32 s0, s0, s3
	s_addc_u32 s1, s1, s6
	v_mov_b32_e32 v3, s1
	v_or_b32_e32 v2, s0, v222
	v_readlane_b32 s0, v252, 19
	v_lshlrev_b64 v[4:5], 10, v[2:3]
	v_readlane_b32 s1, v252, 20
	s_lshl_b32 s2, s2, 2
	s_add_i32 s2, s2, s7
	v_lshl_add_u64 v[4:5], s[0:1], 0, v[4:5]
	s_lshl_b32 s0, s7, 7
	s_ashr_i32 s1, s0, 31
	v_lshl_add_u64 v[4:5], s[0:1], 1, v[4:5]
	v_lshl_add_u64 v[4:5], v[4:5], 0, v[214:215]
	s_ashr_i32 s3, s2, 31
	global_load_dwordx4 v[82:85], v[4:5], off
	global_load_dwordx4 v[86:89], v[4:5], off offset:32
	global_load_dwordx4 v[90:93], v[4:5], off offset:64
	global_load_dwordx4 v[94:97], v[4:5], off offset:96
	global_load_dwordx4 v[98:101], v[4:5], off offset:128
	global_load_dwordx4 v[102:105], v[4:5], off offset:160
	global_load_dwordx4 v[106:109], v[4:5], off offset:192
	global_load_dwordx4 v[110:113], v[4:5], off offset:224
	s_lshl_b64 s[2:3], s[2:3], 16
	v_lshl_add_u64 v[182:183], v[226:227], 0, s[2:3]
	v_mov_b32_e32 v50, v215
	v_mov_b32_e32 v51, v215
	v_lshlrev_b64 v[232:233], 9, v[2:3]
	s_add_u32 s2, s9, s2
	v_mov_b32_e32 v52, v215
	v_mov_b32_e32 v53, v215
	v_mov_b32_e32 v54, v215
	v_mov_b32_e32 v55, v215
	v_mov_b32_e32 v56, v215
	v_mov_b32_e32 v57, v215
	v_mov_b32_e32 v58, v215
	v_mov_b32_e32 v59, v215
	v_mov_b32_e32 v60, v215
	v_mov_b32_e32 v61, v215
	v_mov_b32_e32 v62, v215
	v_mov_b32_e32 v63, v215
	v_mov_b32_e32 v64, v215
	v_mov_b32_e32 v65, v215
	v_mov_b64_e32 v[34:35], v[50:51]
	v_mov_b64_e32 v[18:19], v[50:51]
	v_mov_b64_e32 v[2:3], v[50:51]
	s_mov_b32 s11, 0
	s_addc_u32 s3, s10, s3
	v_mov_b32_e32 v231, 0
	v_mov_b32_e32 v248, 0xff800000
	v_mov_b64_e32 v[36:37], v[52:53]
	v_mov_b64_e32 v[38:39], v[54:55]
	v_mov_b64_e32 v[40:41], v[56:57]
	v_mov_b64_e32 v[42:43], v[58:59]
	v_mov_b64_e32 v[44:45], v[60:61]
	v_mov_b64_e32 v[46:47], v[62:63]
	v_mov_b64_e32 v[48:49], v[64:65]
	v_mov_b64_e32 v[20:21], v[52:53]
	v_mov_b64_e32 v[22:23], v[54:55]
	v_mov_b64_e32 v[24:25], v[56:57]
	v_mov_b64_e32 v[26:27], v[58:59]
	v_mov_b64_e32 v[28:29], v[60:61]
	v_mov_b64_e32 v[30:31], v[62:63]
	v_mov_b64_e32 v[32:33], v[64:65]
	v_mov_b64_e32 v[4:5], v[52:53]
	v_mov_b64_e32 v[6:7], v[54:55]
	v_mov_b64_e32 v[8:9], v[56:57]
	v_mov_b64_e32 v[10:11], v[58:59]
	v_mov_b64_e32 v[12:13], v[60:61]
	v_mov_b64_e32 v[14:15], v[62:63]
	v_mov_b64_e32 v[16:17], v[64:65]
	s_and_b32 s6, s8, 7
	s_lshl_b32 s6, s6, 13
	s_mov_b32 s7, 0
	v_lshl_add_u64 v[182:183], s[6:7], 0, v[182:183]
	global_load_dwordx4 v[114:117], v[182:183], off
	global_load_dwordx4 v[118:121], v[182:183], off offset:1024
	global_load_dwordx4 v[122:125], v[182:183], off offset:2048
	global_load_dwordx4 v[126:129], v[182:183], off offset:3072
	v_add_co_u32_e32 v184, vcc, 0x1000, v182
	s_nop 1
	v_addc_co_u32_e32 v185, vcc, 0, v183, vcc
	global_load_dwordx4 v[130:133], v[184:185], off
	global_load_dwordx4 v[134:137], v[184:185], off offset:1024
	global_load_dwordx4 v[138:141], v[184:185], off offset:2048
	global_load_dwordx4 v[142:145], v[184:185], off offset:3072
	v_lshl_add_u64 v[186:187], s[6:7], 0, v[228:229]
	v_lshl_add_u64 v[186:187], s[2:3], 0, v[186:187]
	v_add_co_u32_e32 v186, vcc, 0x22a00000, v186
	s_nop 1
	v_addc_co_u32_e32 v187, vcc, 0, v187, vcc
	v_add_co_u32_e32 v184, vcc, 0x1000, v186
	s_nop 1
	v_addc_co_u32_e32 v185, vcc, 0, v187, vcc
	global_load_dwordx4 v[146:149], v[186:187], off
	global_load_dwordx4 v[162:165], v[186:187], off offset:16
	global_load_dwordx4 v[150:153], v[186:187], off offset:2048
	global_load_dwordx4 v[166:169], v[186:187], off offset:2064
	global_load_dwordx4 v[154:157], v[184:185], off
	global_load_dwordx4 v[170:173], v[184:185], off offset:16
	global_load_dwordx4 v[158:161], v[184:185], off offset:2048
	global_load_dwordx4 v[174:177], v[184:185], off offset:2064
	v_add_u32_e32 v188, s6, v224
	v_add_u32_e32 v189, 0x10000, v188
	s_waitcnt vmcnt(0)
	ds_write_b128 v188, v[114:117]
	ds_write_b128 v188, v[118:121] offset:1024
	ds_write_b128 v188, v[122:125] offset:2048
	ds_write_b128 v188, v[126:129] offset:3072
	ds_write_b128 v188, v[130:133] offset:4096
	ds_write_b128 v188, v[134:137] offset:5120
	ds_write_b128 v188, v[138:141] offset:6144
	ds_write_b128 v188, v[142:145] offset:7168
	ds_write_b128 v189, v[146:149]
	ds_write_b128 v189, v[162:165] offset:1024
	ds_write_b128 v189, v[150:153] offset:2048
	ds_write_b128 v189, v[166:169] offset:3072
	ds_write_b128 v189, v[154:157] offset:4096
	ds_write_b128 v189, v[170:173] offset:5120
	ds_write_b128 v189, v[158:161] offset:6144
	ds_write_b128 v189, v[174:177] offset:7168
	v_mov_b32_e32 v180, v224
	v_add_u32_e32 v181, 0x10000, v224
	s_waitcnt lgkmcnt(0)
	s_barrier
	ds_read_b128 v[114:117], v180
	ds_read_b128 v[118:121], v180 offset:1024
	ds_read_b128 v[122:125], v180 offset:2048
	ds_read_b128 v[126:129], v180 offset:3072
	ds_read_b128 v[130:133], v180 offset:4096
	ds_read_b128 v[134:137], v180 offset:5120
	ds_read_b128 v[138:141], v180 offset:6144
	ds_read_b128 v[142:145], v180 offset:7168
.Lxa_tile:
	s_waitcnt lgkmcnt(7)
	v_mfma_f32_32x32x16_bf16 v[66:81], v[114:117], v[82:85], 0
	ds_read_b128 v[146:149], v181
	s_waitcnt lgkmcnt(7)
	v_mfma_f32_32x32x16_bf16 v[66:81], v[118:121], v[86:89], v[66:81]
	ds_read_b128 v[162:165], v181 offset:1024
	s_waitcnt lgkmcnt(7)
	v_mfma_f32_32x32x16_bf16 v[66:81], v[122:125], v[90:93], v[66:81]
	ds_read_b128 v[150:153], v181 offset:2048
	s_waitcnt lgkmcnt(7)
	v_mfma_f32_32x32x16_bf16 v[66:81], v[126:129], v[94:97], v[66:81]
	ds_read_b128 v[166:169], v181 offset:3072
	s_waitcnt lgkmcnt(7)
	v_mfma_f32_32x32x16_bf16 v[66:81], v[130:133], v[98:101], v[66:81]
	ds_read_b128 v[154:157], v181 offset:4096
	s_waitcnt lgkmcnt(7)
	v_mfma_f32_32x32x16_bf16 v[66:81], v[134:137], v[102:105], v[66:81]
	ds_read_b128 v[170:173], v181 offset:5120
	s_waitcnt lgkmcnt(7)
	v_mfma_f32_32x32x16_bf16 v[66:81], v[138:141], v[106:109], v[66:81]
	ds_read_b128 v[158:161], v181 offset:6144
	s_waitcnt lgkmcnt(7)
	v_mfma_f32_32x32x16_bf16 v[66:81], v[142:145], v[110:113], v[66:81]
	ds_read_b128 v[174:177], v181 offset:7168
	s_nop 11
	v_max3_f32 v212, v66, v67, v68
	v_max3_f32 v213, v69, v70, v71
	v_max3_f32 v220, v72, v73, v74
	v_max3_f32 v221, v75, v76, v77
	v_max3_f32 v238, v78, v79, v80
	v_max3_f32 v212, v212, v213, v220
	v_max3_f32 v221, v221, v238, v81
	v_max_f32_e32 v212, v212, v221
	ds_bpermute_b32 v213, v247, v212
	v_add_u32_e32 v180, 0x2000, v180
	s_waitcnt lgkmcnt(0)
	ds_read_b128 v[114:117], v180
	ds_read_b128 v[118:121], v180 offset:1024
	ds_read_b128 v[122:125], v180 offset:2048
	ds_read_b128 v[126:129], v180 offset:3072
	ds_read_b128 v[130:133], v180 offset:4096
	ds_read_b128 v[134:137], v180 offset:5120
	ds_read_b128 v[138:141], v180 offset:6144
	ds_read_b128 v[142:145], v180 offset:7168
	v_med3_f32 v212, v212, v213, s89
	v_mul_f32_e32 v212, 0x3e0293ee, v212
	v_max_f32_e32 v213, v248, v248
	v_max_f32_e32 v220, v213, v212
	v_fma_f32 v66, v66, s67, -v220
	v_fma_f32 v67, v67, s67, -v220
	v_fma_f32 v68, v68, s67, -v220
	v_fma_f32 v69, v69, s67, -v220
	v_fma_f32 v70, v70, s67, -v220
	v_fma_f32 v71, v71, s67, -v220
	v_fma_f32 v72, v72, s67, -v220
	v_fma_f32 v73, v73, s67, -v220
	v_fma_f32 v74, v74, s67, -v220
	v_fma_f32 v75, v75, s67, -v220
	v_fma_f32 v76, v76, s67, -v220
	v_fma_f32 v77, v77, s67, -v220
	v_fma_f32 v78, v78, s67, -v220
	v_fma_f32 v79, v79, s67, -v220
	v_fma_f32 v80, v80, s67, -v220
	v_fma_f32 v81, v81, s67, -v220
	v_exp_f32_e32 v66, v66
	v_exp_f32_e32 v67, v67
	v_add_f32_e32 v221, 0, v66
	v_exp_f32_e32 v68, v68
	v_add_f32_e32 v221, v67, v221
	v_exp_f32_e32 v69, v69
	v_add_f32_e32 v221, v68, v221
	v_exp_f32_e32 v70, v70
	v_add_f32_e32 v221, v69, v221
	v_exp_f32_e32 v71, v71
	v_add_f32_e32 v221, v70, v221
	v_exp_f32_e32 v72, v72
	v_add_f32_e32 v221, v71, v221
	v_exp_f32_e32 v73, v73
	v_add_f32_e32 v221, v72, v221
	v_exp_f32_e32 v74, v74
	v_add_f32_e32 v221, v73, v221
	v_exp_f32_e32 v75, v75
	v_add_f32_e32 v221, v74, v221
	v_exp_f32_e32 v76, v76
	v_add_f32_e32 v221, v75, v221
	v_exp_f32_e32 v77, v77
	v_add_f32_e32 v221, v76, v221
	v_exp_f32_e32 v78, v78
	v_add_f32_e32 v221, v77, v221
	v_exp_f32_e32 v79, v79
	v_add_f32_e32 v221, v78, v221
	v_exp_f32_e32 v80, v80
	v_add_f32_e32 v221, v79, v221
	v_exp_f32_e32 v81, v81
	v_add_f32_e32 v221, v80, v221
	v_sub_f32_e32 v213, v248, v220
	v_add_f32_e32 v221, v81, v221
	v_exp_f32_e32 v236, v213
	v_mov_b32_e32 v248, v220
	ds_bpermute_b32 v238, v247, v221
	v_cmp_neq_f32_e32 vcc, 1.0, v236
	s_cbranch_vccz .Lxa_noresc
	v_pk_mul_f32 v[64:65], v[64:65], v[236:237] op_sel_hi:[1,0]
	v_pk_mul_f32 v[62:63], v[62:63], v[236:237] op_sel_hi:[1,0]
	v_pk_mul_f32 v[60:61], v[60:61], v[236:237] op_sel_hi:[1,0]
	v_pk_mul_f32 v[58:59], v[58:59], v[236:237] op_sel_hi:[1,0]
	v_pk_mul_f32 v[56:57], v[56:57], v[236:237] op_sel_hi:[1,0]
	v_pk_mul_f32 v[54:55], v[54:55], v[236:237] op_sel_hi:[1,0]
	v_pk_mul_f32 v[52:53], v[52:53], v[236:237] op_sel_hi:[1,0]
	v_pk_mul_f32 v[50:51], v[50:51], v[236:237] op_sel_hi:[1,0]
	v_pk_mul_f32 v[48:49], v[48:49], v[236:237] op_sel_hi:[1,0]
	v_pk_mul_f32 v[46:47], v[46:47], v[236:237] op_sel_hi:[1,0]
	v_pk_mul_f32 v[44:45], v[44:45], v[236:237] op_sel_hi:[1,0]
	v_pk_mul_f32 v[42:43], v[42:43], v[236:237] op_sel_hi:[1,0]
	v_pk_mul_f32 v[40:41], v[40:41], v[236:237] op_sel_hi:[1,0]
	v_pk_mul_f32 v[38:39], v[38:39], v[236:237] op_sel_hi:[1,0]
	v_pk_mul_f32 v[36:37], v[36:37], v[236:237] op_sel_hi:[1,0]
	v_pk_mul_f32 v[34:35], v[34:35], v[236:237] op_sel_hi:[1,0]
	v_pk_mul_f32 v[32:33], v[32:33], v[236:237] op_sel_hi:[1,0]
	v_pk_mul_f32 v[30:31], v[30:31], v[236:237] op_sel_hi:[1,0]
	v_pk_mul_f32 v[28:29], v[28:29], v[236:237] op_sel_hi:[1,0]
	v_pk_mul_f32 v[26:27], v[26:27], v[236:237] op_sel_hi:[1,0]
	v_pk_mul_f32 v[24:25], v[24:25], v[236:237] op_sel_hi:[1,0]
	v_pk_mul_f32 v[22:23], v[22:23], v[236:237] op_sel_hi:[1,0]
	v_pk_mul_f32 v[20:21], v[20:21], v[236:237] op_sel_hi:[1,0]
	v_pk_mul_f32 v[18:19], v[18:19], v[236:237] op_sel_hi:[1,0]
	v_pk_mul_f32 v[16:17], v[16:17], v[236:237] op_sel_hi:[1,0]
	v_pk_mul_f32 v[14:15], v[14:15], v[236:237] op_sel_hi:[1,0]
	v_pk_mul_f32 v[12:13], v[12:13], v[236:237] op_sel_hi:[1,0]
	v_pk_mul_f32 v[10:11], v[10:11], v[236:237] op_sel_hi:[1,0]
	v_pk_mul_f32 v[8:9], v[8:9], v[236:237] op_sel_hi:[1,0]
	v_pk_mul_f32 v[6:7], v[6:7], v[236:237] op_sel_hi:[1,0]
	v_pk_mul_f32 v[4:5], v[4:5], v[236:237] op_sel_hi:[1,0]
	v_pk_mul_f32 v[2:3], v[2:3], v[236:237] op_sel_hi:[1,0]
.Lxa_noresc:
	s_waitcnt lgkmcnt(0)
	v_add_f32_e32 v221, v221, v238
	v_fmac_f32_e32 v221, v231, v236
	s_nop 0
	v_mov_b32_e32 v231, v221
	v_cvt_pk_bf16_f32 v66, v66, v67
	v_cvt_pk_bf16_f32 v67, v68, v69
	v_cvt_pk_bf16_f32 v68, v70, v71
	v_cvt_pk_bf16_f32 v69, v72, v73
	v_cvt_pk_bf16_f32 v70, v74, v75
	v_cvt_pk_bf16_f32 v71, v76, v77
	v_cvt_pk_bf16_f32 v72, v78, v79
	v_cvt_pk_bf16_f32 v73, v80, v81
	s_nop 1
	v_mfma_f32_32x32x16_bf16 v[50:65], v[146:149], v[66:69], v[50:65]
	v_mfma_f32_32x32x16_bf16 v[34:49], v[150:153], v[66:69], v[34:49]
	v_mfma_f32_32x32x16_bf16 v[18:33], v[154:157], v[66:69], v[18:33]
	v_mfma_f32_32x32x16_bf16 v[2:17], v[158:161], v[66:69], v[2:17]
	v_mfma_f32_32x32x16_bf16 v[50:65], v[162:165], v[70:73], v[50:65]
	v_mfma_f32_32x32x16_bf16 v[34:49], v[166:169], v[70:73], v[34:49]
	v_mfma_f32_32x32x16_bf16 v[18:33], v[170:173], v[70:73], v[18:33]
	v_mfma_f32_32x32x16_bf16 v[2:17], v[174:177], v[70:73], v[2:17]
	v_add_u32_e32 v181, 0x2000, v181
	s_add_i32 s11, s11, 1
	s_cmp_lt_u32 s11, 8
	s_cbranch_scc1 .Lxa_tile
	s_nop 15
	s_branch .LBB0_1510
